# G3 residual epilogue restructured like G5 (gate once, all residual rows up front incl. the fp32-input layer-0 path)
# speedup vs baseline: 1.0185x; 1.0078x over previous
.LBB0_307:
	s_or_b64 exec, exec, s[20:21]
	s_add_i32 s8, s16, 6
	s_cmp_gt_u32 s8, 14
	s_movk_i32 s8, 0x4400
	v_mul_lo_u32 v42, v136, s8
	v_lshl_or_b32 v3, v138, 2, v42
	s_movk_i32 s8, 0x440
	v_mad_u32_u24 v3, v135, s8, v3
	v_add_u32_e32 v4, 0x1000, v3
	v_add_u32_e32 v5, 0x1400, v3
	s_waitcnt vmcnt(0) lgkmcnt(0)
	s_barrier
	ds_write2_b32 v3, v102, v90 offset1:16
	ds_write2_b32 v3, v103, v91 offset0:68 offset1:84
	ds_write2_b32 v3, v104, v92 offset0:136 offset1:152
	ds_write2_b32 v3, v105, v93 offset0:204 offset1:220
	ds_write2_b32 v3, v74, v94 offset0:32 offset1:48
	ds_write2_b32 v3, v75, v95 offset0:100 offset1:116
	ds_write2_b32 v3, v76, v96 offset0:168 offset1:184
	ds_write2_b32 v3, v77, v97 offset0:236 offset1:252
	ds_write2_b32 v4, v98, v78 offset0:64 offset1:80
	ds_write2_b32 v4, v99, v79 offset0:132 offset1:148
	ds_write2_b32 v4, v100, v80 offset0:200 offset1:216
	ds_write2_b32 v5, v101, v81 offset0:12 offset1:28
	ds_write2_b32 v4, v58, v82 offset0:96 offset1:112
	ds_write2_b32 v4, v59, v83 offset0:164 offset1:180
	ds_write2_b32 v4, v60, v84 offset0:232 offset1:248
	ds_write2_b32 v5, v61, v85 offset0:44 offset1:60
	v_add_u32_e32 v4, 0x2000, v3
	v_add_u32_e32 v5, 0x2400, v3
	ds_write2_b32 v4, v86, v62 offset0:128 offset1:144
	ds_write2_b32 v4, v87, v63 offset0:196 offset1:212
	ds_write2_b32 v5, v88, v64 offset0:8 offset1:24
	ds_write2_b32 v5, v89, v65 offset0:76 offset1:92
	ds_write2_b32 v4, v38, v66 offset0:160 offset1:176
	ds_write2_b32 v4, v39, v67 offset0:228 offset1:244
	ds_write2_b32 v5, v40, v68 offset0:40 offset1:56
	ds_write2_b32 v5, v41, v69 offset0:108 offset1:124
	v_add_u32_e32 v4, 0x3000, v3
	v_add_u32_e32 v3, 0x3400, v3
	v_readlane_b32 s8, v254, 46
	ds_write2_b32 v4, v70, v46 offset0:192 offset1:208
	ds_write2_b32 v3, v71, v47 offset0:4 offset1:20
	ds_write2_b32 v3, v72, v48 offset0:72 offset1:88
	ds_write2_b32 v3, v73, v49 offset0:140 offset1:156
	ds_write2_b32 v4, v30, v34 offset0:224 offset1:240
	ds_write2_b32 v3, v31, v35 offset0:36 offset1:52
	ds_write2_b32 v3, v32, v36 offset0:104 offset1:120
	ds_write2_b32 v3, v33, v37 offset0:172 offset1:188
	v_lshl_add_u32 v34, v0, 6, s8
	v_lshrrev_b32_e32 v35, 3, v134
	v_lshlrev_b32_e32 v0, 3, v134
	v_or_b32_e32 v28, v34, v35
	v_lshlrev_b32_e32 v2, 6, v139
	v_and_b32_e32 v0, 56, v0
	v_readlane_b32 s8, v254, 47
	v_add_u32_e32 v30, 0xfffff000, v28
	v_cmp_lt_i32_e64 s[40:41], s1, v28
	v_or3_b32 v18, v2, s8, v0
	v_lshrrev_b32_e32 v2, 10, v30
	v_cndmask_b32_e64 v2, 4, v2, s[40:41]
	s_mul_i32 s8, s18, 5
	v_add_u32_e32 v4, s8, v2
	s_cselect_b64 s[20:21], -1, 0
	v_mov_b64_e32 v[2:3], s[14:15]
	v_mad_i64_i32 v[2:3], s[22:23], v4, s82, v[2:3]
	v_lshlrev_b32_e32 v26, 2, v18
	v_mov_b32_e32 v27, v1
	v_lshl_add_u64 v[10:11], v[2:3], 0, v[26:27]
	s_mov_b64 s[22:23], 0x8602000
	v_lshl_add_u64 v[10:11], v[10:11], 0, s[22:23]
	global_load_dwordx4 v[108:111], v[10:11], off
	global_load_dwordx4 v[112:115], v[10:11], off offset:16
	v_mul_u32_u24_e32 v37, 0x110, v35
	v_lshlrev_b32_e32 v36, 2, v0
	v_add3_u32 v8, v42, v37, v36
	v_lshlrev_b32_e32 v0, 1, v18
	v_mov_b32_e32 v10, v28
	v_ashrrev_i32_e32 v11, 31, v10
	v_lshlrev_b64 v[10:11], 11, v[10:11]
	v_lshl_add_u64 v[10:11], s[66:67], 0, v[10:11]
	v_lshl_add_u64 v[116:117], v[10:11], 0, v[0:1]
	v_or3_b32 v10, v35, v34, 8
	v_ashrrev_i32_e32 v11, 31, v10
	v_lshlrev_b64 v[10:11], 11, v[10:11]
	v_lshl_add_u64 v[10:11], s[66:67], 0, v[10:11]
	v_lshl_add_u64 v[118:119], v[10:11], 0, v[0:1]
	v_or3_b32 v10, v35, v34, 16
	v_ashrrev_i32_e32 v11, 31, v10
	v_lshlrev_b64 v[10:11], 11, v[10:11]
	v_lshl_add_u64 v[10:11], s[66:67], 0, v[10:11]
	v_lshl_add_u64 v[120:121], v[10:11], 0, v[0:1]
	v_or3_b32 v10, v35, v34, 24
	v_ashrrev_i32_e32 v11, 31, v10
	v_lshlrev_b64 v[10:11], 11, v[10:11]
	v_lshl_add_u64 v[10:11], s[66:67], 0, v[10:11]
	v_lshl_add_u64 v[122:123], v[10:11], 0, v[0:1]
	v_or3_b32 v10, v35, v34, 32
	v_ashrrev_i32_e32 v11, 31, v10
	v_lshlrev_b64 v[10:11], 11, v[10:11]
	v_lshl_add_u64 v[10:11], s[66:67], 0, v[10:11]
	v_lshl_add_u64 v[124:125], v[10:11], 0, v[0:1]
	v_or3_b32 v10, v35, v34, 40
	v_ashrrev_i32_e32 v11, 31, v10
	v_lshlrev_b64 v[10:11], 11, v[10:11]
	v_lshl_add_u64 v[10:11], s[66:67], 0, v[10:11]
	v_lshl_add_u64 v[126:127], v[10:11], 0, v[0:1]
	v_or3_b32 v10, v35, v34, 48
	v_ashrrev_i32_e32 v11, 31, v10
	v_lshlrev_b64 v[10:11], 11, v[10:11]
	v_lshl_add_u64 v[10:11], s[66:67], 0, v[10:11]
	v_lshl_add_u64 v[128:129], v[10:11], 0, v[0:1]
	v_or3_b32 v10, v35, v34, 56
	v_ashrrev_i32_e32 v11, 31, v10
	v_lshlrev_b64 v[10:11], 11, v[10:11]
	v_lshl_add_u64 v[10:11], s[66:67], 0, v[10:11]
	v_lshl_add_u64 v[130:131], v[10:11], 0, v[0:1]
	s_and_b64 vcc, exec, s[20:21]
	s_cbranch_vccz .Lg3_from_input
	global_load_dwordx4 v[44:47], v[116:117], off
	global_load_dwordx4 v[48:51], v[118:119], off
	global_load_dwordx4 v[52:55], v[120:121], off
	global_load_dwordx4 v[56:59], v[122:123], off
	global_load_dwordx4 v[60:63], v[124:125], off
	global_load_dwordx4 v[64:67], v[126:127], off
	global_load_dwordx4 v[68:71], v[128:129], off
	global_load_dwordx4 v[72:75], v[130:131], off
	ds_read_b128 v[132:135], v8
	ds_read_b128 v[136:139], v8 offset:16
	ds_read_b128 v[140:143], v8 offset:2176
	ds_read_b128 v[144:147], v8 offset:2192
	s_waitcnt vmcnt(7)
	v_lshlrev_b32_e32 v148, 16, v44
	v_and_b32_e32 v149, 0xffff0000, v44
	v_lshlrev_b32_e32 v150, 16, v45
	v_and_b32_e32 v151, 0xffff0000, v45
	v_lshlrev_b32_e32 v152, 16, v46
	v_and_b32_e32 v153, 0xffff0000, v46
	v_lshlrev_b32_e32 v154, 16, v47
	v_and_b32_e32 v155, 0xffff0000, v47
	s_waitcnt lgkmcnt(2)
	v_pk_fma_f32 v[148:149], v[132:133], v[108:109], v[148:149]
	v_pk_fma_f32 v[150:151], v[134:135], v[110:111], v[150:151]
	v_pk_fma_f32 v[152:153], v[136:137], v[112:113], v[152:153]
	v_pk_fma_f32 v[154:155], v[138:139], v[114:115], v[154:155]
	v_cvt_pk_bf16_f32 v164, v148, v149
	v_cvt_pk_bf16_f32 v165, v150, v151
	v_cvt_pk_bf16_f32 v166, v152, v153
	v_cvt_pk_bf16_f32 v167, v154, v155
	global_store_dwordx4 v[116:117], v[164:167], off
	ds_read_b128 v[132:135], v8 offset:4352
	ds_read_b128 v[136:139], v8 offset:4368
	s_waitcnt vmcnt(7)
	v_lshlrev_b32_e32 v156, 16, v48
	v_and_b32_e32 v157, 0xffff0000, v48
	v_lshlrev_b32_e32 v158, 16, v49
	v_and_b32_e32 v159, 0xffff0000, v49
	v_lshlrev_b32_e32 v160, 16, v50
	v_and_b32_e32 v161, 0xffff0000, v50
	v_lshlrev_b32_e32 v162, 16, v51
	v_and_b32_e32 v163, 0xffff0000, v51
	s_waitcnt lgkmcnt(2)
	v_pk_fma_f32 v[156:157], v[140:141], v[108:109], v[156:157]
	v_pk_fma_f32 v[158:159], v[142:143], v[110:111], v[158:159]
	v_pk_fma_f32 v[160:161], v[144:145], v[112:113], v[160:161]
	v_pk_fma_f32 v[162:163], v[146:147], v[114:115], v[162:163]
	v_cvt_pk_bf16_f32 v168, v156, v157
	v_cvt_pk_bf16_f32 v169, v158, v159
	v_cvt_pk_bf16_f32 v170, v160, v161
	v_cvt_pk_bf16_f32 v171, v162, v163
	global_store_dwordx4 v[118:119], v[168:171], off
	ds_read_b128 v[140:143], v8 offset:6528
	ds_read_b128 v[144:147], v8 offset:6544
	s_waitcnt vmcnt(7)
	v_lshlrev_b32_e32 v148, 16, v52
	v_and_b32_e32 v149, 0xffff0000, v52
	v_lshlrev_b32_e32 v150, 16, v53
	v_and_b32_e32 v151, 0xffff0000, v53
	v_lshlrev_b32_e32 v152, 16, v54
	v_and_b32_e32 v153, 0xffff0000, v54
	v_lshlrev_b32_e32 v154, 16, v55
	v_and_b32_e32 v155, 0xffff0000, v55
	s_waitcnt lgkmcnt(2)
	v_pk_fma_f32 v[148:149], v[132:133], v[108:109], v[148:149]
	v_pk_fma_f32 v[150:151], v[134:135], v[110:111], v[150:151]
	v_pk_fma_f32 v[152:153], v[136:137], v[112:113], v[152:153]
	v_pk_fma_f32 v[154:155], v[138:139], v[114:115], v[154:155]
	v_cvt_pk_bf16_f32 v164, v148, v149
	v_cvt_pk_bf16_f32 v165, v150, v151
	v_cvt_pk_bf16_f32 v166, v152, v153
	v_cvt_pk_bf16_f32 v167, v154, v155
	global_store_dwordx4 v[120:121], v[164:167], off
	ds_read_b128 v[132:135], v8 offset:8704
	ds_read_b128 v[136:139], v8 offset:8720
	s_waitcnt vmcnt(7)
	v_lshlrev_b32_e32 v156, 16, v56
	v_and_b32_e32 v157, 0xffff0000, v56
	v_lshlrev_b32_e32 v158, 16, v57
	v_and_b32_e32 v159, 0xffff0000, v57
	v_lshlrev_b32_e32 v160, 16, v58
	v_and_b32_e32 v161, 0xffff0000, v58
	v_lshlrev_b32_e32 v162, 16, v59
	v_and_b32_e32 v163, 0xffff0000, v59
	s_waitcnt lgkmcnt(2)
	v_pk_fma_f32 v[156:157], v[140:141], v[108:109], v[156:157]
	v_pk_fma_f32 v[158:159], v[142:143], v[110:111], v[158:159]
	v_pk_fma_f32 v[160:161], v[144:145], v[112:113], v[160:161]
	v_pk_fma_f32 v[162:163], v[146:147], v[114:115], v[162:163]
	v_cvt_pk_bf16_f32 v168, v156, v157
	v_cvt_pk_bf16_f32 v169, v158, v159
	v_cvt_pk_bf16_f32 v170, v160, v161
	v_cvt_pk_bf16_f32 v171, v162, v163
	global_store_dwordx4 v[122:123], v[168:171], off
	ds_read_b128 v[140:143], v8 offset:10880
	ds_read_b128 v[144:147], v8 offset:10896
	s_waitcnt vmcnt(7)
	v_lshlrev_b32_e32 v148, 16, v60
	v_and_b32_e32 v149, 0xffff0000, v60
	v_lshlrev_b32_e32 v150, 16, v61
	v_and_b32_e32 v151, 0xffff0000, v61
	v_lshlrev_b32_e32 v152, 16, v62
	v_and_b32_e32 v153, 0xffff0000, v62
	v_lshlrev_b32_e32 v154, 16, v63
	v_and_b32_e32 v155, 0xffff0000, v63
	s_waitcnt lgkmcnt(2)
	v_pk_fma_f32 v[148:149], v[132:133], v[108:109], v[148:149]
	v_pk_fma_f32 v[150:151], v[134:135], v[110:111], v[150:151]
	v_pk_fma_f32 v[152:153], v[136:137], v[112:113], v[152:153]
	v_pk_fma_f32 v[154:155], v[138:139], v[114:115], v[154:155]
	v_cvt_pk_bf16_f32 v164, v148, v149
	v_cvt_pk_bf16_f32 v165, v150, v151
	v_cvt_pk_bf16_f32 v166, v152, v153
	v_cvt_pk_bf16_f32 v167, v154, v155
	global_store_dwordx4 v[124:125], v[164:167], off
	ds_read_b128 v[132:135], v8 offset:13056
	ds_read_b128 v[136:139], v8 offset:13072
	s_waitcnt vmcnt(7)
	v_lshlrev_b32_e32 v156, 16, v64
	v_and_b32_e32 v157, 0xffff0000, v64
	v_lshlrev_b32_e32 v158, 16, v65
	v_and_b32_e32 v159, 0xffff0000, v65
	v_lshlrev_b32_e32 v160, 16, v66
	v_and_b32_e32 v161, 0xffff0000, v66
	v_lshlrev_b32_e32 v162, 16, v67
	v_and_b32_e32 v163, 0xffff0000, v67
	s_waitcnt lgkmcnt(2)
	v_pk_fma_f32 v[156:157], v[140:141], v[108:109], v[156:157]
	v_pk_fma_f32 v[158:159], v[142:143], v[110:111], v[158:159]
	v_pk_fma_f32 v[160:161], v[144:145], v[112:113], v[160:161]
	v_pk_fma_f32 v[162:163], v[146:147], v[114:115], v[162:163]
	v_cvt_pk_bf16_f32 v168, v156, v157
	v_cvt_pk_bf16_f32 v169, v158, v159
	v_cvt_pk_bf16_f32 v170, v160, v161
	v_cvt_pk_bf16_f32 v171, v162, v163
	global_store_dwordx4 v[126:127], v[168:171], off
	ds_read_b128 v[140:143], v8 offset:15232
	ds_read_b128 v[144:147], v8 offset:15248
	s_waitcnt vmcnt(7)
	v_lshlrev_b32_e32 v148, 16, v68
	v_and_b32_e32 v149, 0xffff0000, v68
	v_lshlrev_b32_e32 v150, 16, v69
	v_and_b32_e32 v151, 0xffff0000, v69
	v_lshlrev_b32_e32 v152, 16, v70
	v_and_b32_e32 v153, 0xffff0000, v70
	v_lshlrev_b32_e32 v154, 16, v71
	v_and_b32_e32 v155, 0xffff0000, v71
	s_waitcnt lgkmcnt(2)
	v_pk_fma_f32 v[148:149], v[132:133], v[108:109], v[148:149]
	v_pk_fma_f32 v[150:151], v[134:135], v[110:111], v[150:151]
	v_pk_fma_f32 v[152:153], v[136:137], v[112:113], v[152:153]
	v_pk_fma_f32 v[154:155], v[138:139], v[114:115], v[154:155]
	v_cvt_pk_bf16_f32 v164, v148, v149
	v_cvt_pk_bf16_f32 v165, v150, v151
	v_cvt_pk_bf16_f32 v166, v152, v153
	v_cvt_pk_bf16_f32 v167, v154, v155
	global_store_dwordx4 v[128:129], v[164:167], off
	s_waitcnt vmcnt(7)
	v_lshlrev_b32_e32 v156, 16, v72
	v_and_b32_e32 v157, 0xffff0000, v72
	v_lshlrev_b32_e32 v158, 16, v73
	v_and_b32_e32 v159, 0xffff0000, v73
	v_lshlrev_b32_e32 v160, 16, v74
	v_and_b32_e32 v161, 0xffff0000, v74
	v_lshlrev_b32_e32 v162, 16, v75
	v_and_b32_e32 v163, 0xffff0000, v75
	s_waitcnt lgkmcnt(0)
	v_pk_fma_f32 v[156:157], v[140:141], v[108:109], v[156:157]
	v_pk_fma_f32 v[158:159], v[142:143], v[110:111], v[158:159]
	v_pk_fma_f32 v[160:161], v[144:145], v[112:113], v[160:161]
	v_pk_fma_f32 v[162:163], v[146:147], v[114:115], v[162:163]
	v_cvt_pk_bf16_f32 v168, v156, v157
	v_cvt_pk_bf16_f32 v169, v158, v159
	v_cvt_pk_bf16_f32 v170, v160, v161
	v_cvt_pk_bf16_f32 v171, v162, v163
	global_store_dwordx4 v[130:131], v[168:171], off
	s_branch .LBB0_372
.Lg3_from_input:
	v_readlane_b32 s36, v254, 32
	v_readlane_b32 s37, v254, 33
	v_readlane_b32 s38, v254, 34
	v_readlane_b32 s39, v254, 35
	s_nop 3
	v_mov_b32_e32 v12, s36
	v_mov_b32_e32 v13, s37
	v_mov_b32_e32 v14, s38
	v_mov_b32_e32 v15, s39
	v_cndmask_b32_e64 v12, v12, v14, s[40:41]
	v_cndmask_b32_e64 v13, v13, v15, s[40:41]
	v_mov_b32_e32 v10, v28
	v_add_u32_e32 v11, 0xfffff000, v10
	v_cndmask_b32_e64 v10, v10, v11, s[40:41]
	v_mov_b32_e32 v11, v1
	v_lshlrev_b64 v[10:11], 12, v[10:11]
	v_lshl_add_u64 v[10:11], v[12:13], 0, v[10:11]
	v_lshl_add_u64 v[10:11], v[10:11], 0, v[26:27]
	global_load_dwordx4 v[44:47], v[10:11], off nt
	global_load_dwordx4 v[48:51], v[10:11], off offset:16 nt
	v_or3_b32 v10, v35, v34, 8
	v_add_u32_e32 v11, 0xfffff000, v10
	v_cndmask_b32_e64 v10, v10, v11, s[40:41]
	v_mov_b32_e32 v11, v1
	v_lshlrev_b64 v[10:11], 12, v[10:11]
	v_lshl_add_u64 v[10:11], v[12:13], 0, v[10:11]
	v_lshl_add_u64 v[10:11], v[10:11], 0, v[26:27]
	global_load_dwordx4 v[52:55], v[10:11], off nt
	global_load_dwordx4 v[56:59], v[10:11], off offset:16 nt
	v_or3_b32 v10, v35, v34, 16
	v_add_u32_e32 v11, 0xfffff000, v10
	v_cndmask_b32_e64 v10, v10, v11, s[40:41]
	v_mov_b32_e32 v11, v1
	v_lshlrev_b64 v[10:11], 12, v[10:11]
	v_lshl_add_u64 v[10:11], v[12:13], 0, v[10:11]
	v_lshl_add_u64 v[10:11], v[10:11], 0, v[26:27]
	global_load_dwordx4 v[60:63], v[10:11], off nt
	global_load_dwordx4 v[64:67], v[10:11], off offset:16 nt
	v_or3_b32 v10, v35, v34, 24
	v_add_u32_e32 v11, 0xfffff000, v10
	v_cndmask_b32_e64 v10, v10, v11, s[40:41]
	v_mov_b32_e32 v11, v1
	v_lshlrev_b64 v[10:11], 12, v[10:11]
	v_lshl_add_u64 v[10:11], v[12:13], 0, v[10:11]
	v_lshl_add_u64 v[10:11], v[10:11], 0, v[26:27]
	global_load_dwordx4 v[68:71], v[10:11], off nt
	global_load_dwordx4 v[72:75], v[10:11], off offset:16 nt
	v_or3_b32 v10, v35, v34, 32
	v_add_u32_e32 v11, 0xfffff000, v10
	v_cndmask_b32_e64 v10, v10, v11, s[40:41]
	v_mov_b32_e32 v11, v1
	v_lshlrev_b64 v[10:11], 12, v[10:11]
	v_lshl_add_u64 v[10:11], v[12:13], 0, v[10:11]
	v_lshl_add_u64 v[10:11], v[10:11], 0, v[26:27]
	global_load_dwordx4 v[76:79], v[10:11], off nt
	global_load_dwordx4 v[80:83], v[10:11], off offset:16 nt
	v_or3_b32 v10, v35, v34, 40
	v_add_u32_e32 v11, 0xfffff000, v10
	v_cndmask_b32_e64 v10, v10, v11, s[40:41]
	v_mov_b32_e32 v11, v1
	v_lshlrev_b64 v[10:11], 12, v[10:11]
	v_lshl_add_u64 v[10:11], v[12:13], 0, v[10:11]
	v_lshl_add_u64 v[10:11], v[10:11], 0, v[26:27]
	global_load_dwordx4 v[84:87], v[10:11], off nt
	global_load_dwordx4 v[88:91], v[10:11], off offset:16 nt
	v_or3_b32 v10, v35, v34, 48
	v_add_u32_e32 v11, 0xfffff000, v10
	v_cndmask_b32_e64 v10, v10, v11, s[40:41]
	v_mov_b32_e32 v11, v1
	v_lshlrev_b64 v[10:11], 12, v[10:11]
	v_lshl_add_u64 v[10:11], v[12:13], 0, v[10:11]
	v_lshl_add_u64 v[10:11], v[10:11], 0, v[26:27]
	global_load_dwordx4 v[92:95], v[10:11], off nt
	global_load_dwordx4 v[96:99], v[10:11], off offset:16 nt
	v_or3_b32 v10, v35, v34, 56
	v_add_u32_e32 v11, 0xfffff000, v10
	v_cndmask_b32_e64 v10, v10, v11, s[40:41]
	v_mov_b32_e32 v11, v1
	v_lshlrev_b64 v[10:11], 12, v[10:11]
	v_lshl_add_u64 v[10:11], v[12:13], 0, v[10:11]
	v_lshl_add_u64 v[10:11], v[10:11], 0, v[26:27]
	global_load_dwordx4 v[100:103], v[10:11], off nt
	global_load_dwordx4 v[104:107], v[10:11], off offset:16 nt
	ds_read_b128 v[132:135], v8
	ds_read_b128 v[136:139], v8 offset:16
	ds_read_b128 v[140:143], v8 offset:2176
	ds_read_b128 v[144:147], v8 offset:2192
	s_waitcnt vmcnt(14)
	s_waitcnt lgkmcnt(2)
	v_pk_fma_f32 v[148:149], v[132:133], v[108:109], v[44:45]
	v_pk_fma_f32 v[150:151], v[134:135], v[110:111], v[46:47]
	v_pk_fma_f32 v[152:153], v[136:137], v[112:113], v[48:49]
	v_pk_fma_f32 v[154:155], v[138:139], v[114:115], v[50:51]
	v_cvt_pk_bf16_f32 v164, v148, v149
	v_cvt_pk_bf16_f32 v165, v150, v151
	v_cvt_pk_bf16_f32 v166, v152, v153
	v_cvt_pk_bf16_f32 v167, v154, v155
	global_store_dwordx4 v[116:117], v[164:167], off
	ds_read_b128 v[132:135], v8 offset:4352
	ds_read_b128 v[136:139], v8 offset:4368
	s_waitcnt vmcnt(13)
	s_waitcnt lgkmcnt(2)
	v_pk_fma_f32 v[156:157], v[140:141], v[108:109], v[52:53]
	v_pk_fma_f32 v[158:159], v[142:143], v[110:111], v[54:55]
	v_pk_fma_f32 v[160:161], v[144:145], v[112:113], v[56:57]
	v_pk_fma_f32 v[162:163], v[146:147], v[114:115], v[58:59]
	v_cvt_pk_bf16_f32 v168, v156, v157
	v_cvt_pk_bf16_f32 v169, v158, v159
	v_cvt_pk_bf16_f32 v170, v160, v161
	v_cvt_pk_bf16_f32 v171, v162, v163
	global_store_dwordx4 v[118:119], v[168:171], off
	ds_read_b128 v[140:143], v8 offset:6528
	ds_read_b128 v[144:147], v8 offset:6544
	s_waitcnt vmcnt(12)
	s_waitcnt lgkmcnt(2)
	v_pk_fma_f32 v[148:149], v[132:133], v[108:109], v[60:61]
	v_pk_fma_f32 v[150:151], v[134:135], v[110:111], v[62:63]
	v_pk_fma_f32 v[152:153], v[136:137], v[112:113], v[64:65]
	v_pk_fma_f32 v[154:155], v[138:139], v[114:115], v[66:67]
	v_cvt_pk_bf16_f32 v164, v148, v149
	v_cvt_pk_bf16_f32 v165, v150, v151
	v_cvt_pk_bf16_f32 v166, v152, v153
	v_cvt_pk_bf16_f32 v167, v154, v155
	global_store_dwordx4 v[120:121], v[164:167], off
	ds_read_b128 v[132:135], v8 offset:8704
	ds_read_b128 v[136:139], v8 offset:8720
	s_waitcnt vmcnt(11)
	s_waitcnt lgkmcnt(2)
	v_pk_fma_f32 v[156:157], v[140:141], v[108:109], v[68:69]
	v_pk_fma_f32 v[158:159], v[142:143], v[110:111], v[70:71]
	v_pk_fma_f32 v[160:161], v[144:145], v[112:113], v[72:73]
	v_pk_fma_f32 v[162:163], v[146:147], v[114:115], v[74:75]
	v_cvt_pk_bf16_f32 v168, v156, v157
	v_cvt_pk_bf16_f32 v169, v158, v159
	v_cvt_pk_bf16_f32 v170, v160, v161
	v_cvt_pk_bf16_f32 v171, v162, v163
	global_store_dwordx4 v[122:123], v[168:171], off
	ds_read_b128 v[140:143], v8 offset:10880
	ds_read_b128 v[144:147], v8 offset:10896
	s_waitcnt vmcnt(10)
	s_waitcnt lgkmcnt(2)
	v_pk_fma_f32 v[148:149], v[132:133], v[108:109], v[76:77]
	v_pk_fma_f32 v[150:151], v[134:135], v[110:111], v[78:79]
	v_pk_fma_f32 v[152:153], v[136:137], v[112:113], v[80:81]
	v_pk_fma_f32 v[154:155], v[138:139], v[114:115], v[82:83]
	v_cvt_pk_bf16_f32 v164, v148, v149
	v_cvt_pk_bf16_f32 v165, v150, v151
	v_cvt_pk_bf16_f32 v166, v152, v153
	v_cvt_pk_bf16_f32 v167, v154, v155
	global_store_dwordx4 v[124:125], v[164:167], off
	ds_read_b128 v[132:135], v8 offset:13056
	ds_read_b128 v[136:139], v8 offset:13072
	s_waitcnt vmcnt(9)
	s_waitcnt lgkmcnt(2)
	v_pk_fma_f32 v[156:157], v[140:141], v[108:109], v[84:85]
	v_pk_fma_f32 v[158:159], v[142:143], v[110:111], v[86:87]
	v_pk_fma_f32 v[160:161], v[144:145], v[112:113], v[88:89]
	v_pk_fma_f32 v[162:163], v[146:147], v[114:115], v[90:91]
	v_cvt_pk_bf16_f32 v168, v156, v157
	v_cvt_pk_bf16_f32 v169, v158, v159
	v_cvt_pk_bf16_f32 v170, v160, v161
	v_cvt_pk_bf16_f32 v171, v162, v163
	global_store_dwordx4 v[126:127], v[168:171], off
	ds_read_b128 v[140:143], v8 offset:15232
	ds_read_b128 v[144:147], v8 offset:15248
	s_waitcnt vmcnt(8)
	s_waitcnt lgkmcnt(2)
	v_pk_fma_f32 v[148:149], v[132:133], v[108:109], v[92:93]
	v_pk_fma_f32 v[150:151], v[134:135], v[110:111], v[94:95]
	v_pk_fma_f32 v[152:153], v[136:137], v[112:113], v[96:97]
	v_pk_fma_f32 v[154:155], v[138:139], v[114:115], v[98:99]
	v_cvt_pk_bf16_f32 v164, v148, v149
	v_cvt_pk_bf16_f32 v165, v150, v151
	v_cvt_pk_bf16_f32 v166, v152, v153
	v_cvt_pk_bf16_f32 v167, v154, v155
	global_store_dwordx4 v[128:129], v[164:167], off
	s_waitcnt vmcnt(7)
	s_waitcnt lgkmcnt(0)
	v_pk_fma_f32 v[156:157], v[140:141], v[108:109], v[100:101]
	v_pk_fma_f32 v[158:159], v[142:143], v[110:111], v[102:103]
	v_pk_fma_f32 v[160:161], v[144:145], v[112:113], v[104:105]
	v_pk_fma_f32 v[162:163], v[146:147], v[114:115], v[106:107]
	v_cvt_pk_bf16_f32 v168, v156, v157
	v_cvt_pk_bf16_f32 v169, v158, v159
	v_cvt_pk_bf16_f32 v170, v160, v161
	v_cvt_pk_bf16_f32 v171, v162, v163
	global_store_dwordx4 v[130:131], v[168:171], off
